# attention: V^T LDS tile re-laid (144B rows, 4-key blocks permuted) so each PV fragment is one ds_read_b128 instead of ds_read2_b64; ds_bpermute max-exchange -> v_permlane32_swap; K/V tile ds_writes mo
# speedup vs baseline: 1.0308x; 1.0191x over previous
.LBB0_715:
	s_or_b64 exec, exec, s[44:45]
	s_add_i32 s44, s64, s63
	v_add_u32_e32 v44, s16, v166
	s_ashr_i32 s45, s44, 31
	s_waitcnt lgkmcnt(0)
	ds_read_b128 v[32:35], v44 offset:45056
	s_lshl_b64 s[44:45], s[44:45], 11
	s_add_u32 s44, s0, s44
	s_addc_u32 s45, s1, s45
	v_mov_b32_e32 v165, v81
	v_lshl_add_u64 v[36:37], v[164:165], 1, s[44:45]
	v_lshlrev_b32_e32 v80, 1, v186
	v_mov_b32_e32 v42, v0
	v_mov_b32_e32 v43, v16
	v_lshl_add_u64 v[40:41], v[36:37], 0, v[80:81]
	ds_read_b128 v[36:39], v44 offset:45088
	s_waitcnt lgkmcnt(1)
	v_pk_mul_f32 v[42:43], v[42:43], v[32:33] op_sel_hi:[1,0]
	v_lshlrev_b32_e32 v80, 13, v185
	v_cvt_pk_bf16_f32 v0, v42, v43
	v_lshl_add_u64 v[40:41], v[40:41], 0, v[80:81]
	v_mov_b32_e32 v16, v1
	global_store_short v[40:41], v0, off
	global_store_short_d16_hi v[40:41], v0, off offset:64
	v_pk_mul_f32 v[0:1], v[16:17], v[32:33] op_sel:[0,1]
	s_movk_i32 s16, 0x1000
	v_cvt_pk_bf16_f32 v0, v0, v1
	global_store_short v[40:41], v0, off offset:2048
	global_store_short_d16_hi v[40:41], v0, off offset:2112
	v_mov_b32_e32 v0, v2
	v_mov_b32_e32 v1, v18
	v_pk_mul_f32 v[0:1], v[0:1], v[34:35] op_sel_hi:[1,0]
	v_mov_b32_e32 v18, v3
	v_cvt_pk_bf16_f32 v2, v0, v1
	v_add_co_u32_e32 v0, vcc, s16, v40
	s_movk_i32 s16, 0x4000
	s_nop 0
	v_addc_co_u32_e32 v1, vcc, 0, v41, vcc
	global_store_short v[0:1], v2, off
	global_store_short_d16_hi v[0:1], v2, off offset:64
	v_mov_b32_e32 v2, v35
	v_pk_mul_f32 v[2:3], v[18:19], v[2:3] op_sel_hi:[1,0]
	s_nop 0
	v_cvt_pk_bf16_f32 v2, v2, v3
	global_store_short v[0:1], v2, off offset:2048
	global_store_short_d16_hi v[0:1], v2, off offset:2112
	v_mov_b32_e32 v0, v4
	v_mov_b32_e32 v1, v20
	s_waitcnt lgkmcnt(0)
	v_pk_mul_f32 v[0:1], v[0:1], v[36:37] op_sel_hi:[1,0]
	v_mov_b32_e32 v20, v5
	v_cvt_pk_bf16_f32 v2, v0, v1
	v_add_co_u32_e32 v0, vcc, s16, v40
	s_movk_i32 s16, 0x5000
	s_nop 0
	v_addc_co_u32_e32 v1, vcc, 0, v41, vcc
	v_add_co_u32_e32 v16, vcc, s16, v40
	s_mov_b32 s16, 0x9000
	s_nop 0
	v_addc_co_u32_e32 v17, vcc, 0, v41, vcc
	global_store_short v[16:17], v2, off offset:-4096
	global_store_short_d16_hi v[0:1], v2, off offset:64
	v_pk_mul_f32 v[2:3], v[20:21], v[36:37] op_sel:[0,1]
	s_nop 0
	v_cvt_pk_bf16_f32 v2, v2, v3
	global_store_short v[0:1], v2, off offset:2048
	global_store_short_d16_hi v[0:1], v2, off offset:2112
	v_mov_b32_e32 v0, v6
	v_mov_b32_e32 v1, v22
	v_pk_mul_f32 v[0:1], v[0:1], v[38:39] op_sel_hi:[1,0]
	v_mov_b32_e32 v22, v7
	v_cvt_pk_bf16_f32 v0, v0, v1
	global_store_short v[16:17], v0, off
	global_store_short_d16_hi v[16:17], v0, off offset:64
	v_mov_b32_e32 v0, v39
	v_pk_mul_f32 v[0:1], v[22:23], v[0:1] op_sel_hi:[1,0]
	s_nop 0
	v_cvt_pk_bf16_f32 v4, v0, v1
	ds_read_b128 v[0:3], v44 offset:45120
	global_store_short v[16:17], v4, off offset:2048
	global_store_short_d16_hi v[16:17], v4, off offset:2112
	v_mov_b32_e32 v16, v8
	v_mov_b32_e32 v17, v24
	ds_read_b128 v[4:7], v44 offset:45152
	s_waitcnt lgkmcnt(1)
	v_pk_mul_f32 v[16:17], v[16:17], v[0:1] op_sel_hi:[1,0]
	v_mov_b32_e32 v24, v9
	v_cvt_pk_bf16_f32 v8, v16, v17
	v_add_co_u32_e32 v16, vcc, s27, v40
	v_pk_mul_f32 v[0:1], v[24:25], v[0:1] op_sel:[0,1]
	s_nop 0
	v_addc_co_u32_e32 v17, vcc, 0, v41, vcc
	v_add_co_u32_e32 v18, vcc, s16, v40
	v_cvt_pk_bf16_f32 v0, v0, v1
	s_nop 0
	v_addc_co_u32_e32 v19, vcc, 0, v41, vcc
	global_store_short v[18:19], v8, off offset:-4096
	global_store_short_d16_hi v[16:17], v8, off offset:64
	global_store_short v[16:17], v0, off offset:2048
	global_store_short_d16_hi v[16:17], v0, off offset:2112
	v_mov_b32_e32 v0, v10
	v_mov_b32_e32 v1, v26
	v_pk_mul_f32 v[0:1], v[0:1], v[2:3] op_sel_hi:[1,0]
	v_mov_b32_e32 v26, v11
	v_cvt_pk_bf16_f32 v0, v0, v1
	global_store_short v[18:19], v0, off
	global_store_short_d16_hi v[18:19], v0, off offset:64
	v_mov_b32_e32 v0, v3
	v_pk_mul_f32 v[0:1], v[26:27], v[0:1] op_sel_hi:[1,0]
	s_mov_b32 s16, 0xc000
	v_cvt_pk_bf16_f32 v0, v0, v1
	global_store_short v[18:19], v0, off offset:2048
	global_store_short_d16_hi v[18:19], v0, off offset:2112
	v_mov_b32_e32 v0, v12
	v_mov_b32_e32 v1, v28
	s_waitcnt lgkmcnt(0)
	v_pk_mul_f32 v[0:1], v[0:1], v[4:5] op_sel_hi:[1,0]
	v_mov_b32_e32 v28, v13
	v_cvt_pk_bf16_f32 v2, v0, v1
	v_add_co_u32_e32 v0, vcc, s16, v40
	s_nop 1
	v_addc_co_u32_e32 v1, vcc, 0, v41, vcc
	global_store_short v[0:1], v2, off
	global_store_short_d16_hi v[0:1], v2, off offset:64
	v_pk_mul_f32 v[2:3], v[28:29], v[4:5] op_sel:[0,1]
	s_nop 0
	v_cvt_pk_bf16_f32 v2, v2, v3
	global_store_short v[0:1], v2, off offset:2048
	global_store_short_d16_hi v[0:1], v2, off offset:2112
	v_mov_b32_e32 v0, v14
	v_mov_b32_e32 v1, v30
	v_pk_mul_f32 v[0:1], v[0:1], v[6:7] op_sel_hi:[1,0]
	v_mov_b32_e32 v30, v15
	v_cvt_pk_bf16_f32 v2, v0, v1
	v_add_co_u32_e32 v0, vcc, 0xd000, v40
	s_nop 1
	v_addc_co_u32_e32 v1, vcc, 0, v41, vcc
	global_store_short v[0:1], v2, off
	global_store_short_d16_hi v[0:1], v2, off offset:64
	v_mov_b32_e32 v2, v7
	v_pk_mul_f32 v[2:3], v[30:31], v[2:3] op_sel_hi:[1,0]
	s_nop 0
	v_cvt_pk_bf16_f32 v2, v2, v3
	global_store_short v[0:1], v2, off offset:2048
	global_store_short_d16_hi v[0:1], v2, off offset:2112

.LBB0_731:
	s_or_b64 exec, exec, s[46:47]
	global_load_dwordx4 v[56:59], v[14:15], off offset:128
	v_mul_lo_u32 v13, v13, s33
	v_mul_lo_u32 v18, v18, s33
	v_lshl_add_u32 v13, v19, 4, v13
	v_add3_u32 v187, 0, v18, v12
	v_add_u32_e32 v167, 0, v13
	ds_write_b128 v187, v[0:3]
	s_and_saveexec_b64 s[46:47], s[44:45]
	ds_write_b128 v167, v[4:7]
	s_or_b64 exec, exec, s[46:47]
	s_movk_i32 s16, 0x90
	v_mul_lo_u32 v0, v20, s16
	v_and_b32_e32 v188, 0x60, v132
	v_add_u32_e32 v188, v188, v0
	v_and_b32_e32 v0, 16, v132
	v_lshrrev_b32_e32 v0, 1, v0
	v_add_u32_e32 v188, v188, v0
	v_add_u32_e32 v188, 0x6800, v188
	v_lshl_add_u64 v[0:1], v[16:17], 0, v[80:81]
	s_waitcnt vmcnt(2)
	ds_write2_b64 v188, v[8:9], v[10:11] offset1:2
	s_waitcnt lgkmcnt(0)
	s_barrier
	global_load_dwordx4 v[112:115], v[0:1], off
	s_waitcnt vmcnt(2)
	v_mov_b64_e32 v[110:111], v[50:51]
	v_mov_b64_e32 v[108:109], v[48:49]
	s_and_saveexec_b64 s[46:47], s[44:45]
	s_cbranch_execz .LBB0_735
	v_lshlrev_b32_e32 v0, 2, v130
	v_mov_b32_e32 v1, v81
	v_lshl_add_u64 v[0:1], v[128:129], 0, v[0:1]
	global_load_dwordx4 v[108:111], v[0:1], off
.LBB0_735:
	s_or_b64 exec, exec, s[46:47]
	global_load_dwordx4 v[116:119], v[14:15], off offset:256
	v_lshlrev_b32_e32 v0, 3, v185
	v_mad_u32_u24 v1, v186, s33, 0
	v_mul_i32_i24_e32 v2, 0xffffffc0, v186
	v_add_u32_e32 v189, v1, v166
	v_add3_u32 v165, v1, v2, v166
	s_cmp_lt_i32 s66, 0
	s_cbranch_scc1 .LBB0_737
	ds_read_b128 v[0:3], v189
	ds_read_b128 v[32:35], v189 offset:32
	ds_read_b128 v[16:19], v189 offset:6656
	ds_read_b128 v[36:39], v189 offset:6688
	ds_read_b128 v[40:43], v189 offset:64
	ds_read_b128 v[44:47], v189 offset:96
	ds_read_b128 v[60:63], v189 offset:6720
	ds_read_b128 v[64:67], v189 offset:6752
	ds_read_b128 v[68:71], v189 offset:128
	ds_read_b128 v[72:75], v189 offset:160
	ds_read_b128 v[76:79], v189 offset:6784
	ds_read_b128 v[120:123], v189 offset:6816
	s_waitcnt lgkmcnt(11)
	v_mfma_f32_32x32x16_bf16 v[0:15], v[0:3], v[104:107], 0
	s_waitcnt lgkmcnt(9)
	v_mfma_f32_32x32x16_bf16 v[16:31], v[16:19], v[104:107], 0
	v_mfma_f32_32x32x16_bf16 v[0:15], v[32:35], v[100:103], v[0:15]
	v_add_u32_e32 v32, 0x7800, v165
	v_add_u32_e32 v33, 0x6800, v165
	s_waitcnt lgkmcnt(8)
	v_mfma_f32_32x32x16_bf16 v[16:31], v[36:39], v[100:103], v[16:31]
	s_waitcnt lgkmcnt(7)
	v_mfma_f32_32x32x16_bf16 v[0:15], v[40:43], v[96:99], v[0:15]
	s_waitcnt lgkmcnt(5)
	v_mfma_f32_32x32x16_bf16 v[16:31], v[60:63], v[96:99], v[16:31]
	v_mfma_f32_32x32x16_bf16 v[0:15], v[44:47], v[92:95], v[0:15]
	s_waitcnt lgkmcnt(4)
	v_mfma_f32_32x32x16_bf16 v[16:31], v[64:67], v[92:95], v[16:31]
	s_waitcnt lgkmcnt(3)
	v_mfma_f32_32x32x16_bf16 v[0:15], v[68:71], v[88:91], v[0:15]
	ds_read_b128 v[68:71], v32 offset:512
	s_waitcnt lgkmcnt(2)
	v_mfma_f32_32x32x16_bf16 v[16:31], v[76:79], v[88:91], v[16:31]
	v_mfma_f32_32x32x16_bf16 v[0:15], v[72:75], v[84:87], v[0:15]
	ds_read_b128 v[72:75], v33
	ds_read_b128 v[64:67], v33 offset:32
	ds_read_b128 v[60:63], v32 offset:544
	ds_read_b128 v[44:47], v33 offset:64
	ds_read_b128 v[40:43], v32 offset:576
	ds_read_b128 v[36:39], v33 offset:96
	ds_read_b128 v[32:35], v32 offset:608
	s_waitcnt lgkmcnt(8)
	v_mfma_f32_32x32x16_bf16 v[16:31], v[120:123], v[84:87], v[16:31]
	s_nop 2
	v_max_f32_e32 v76, v1, v1
	v_max_f32_e32 v77, v0, v0
	v_max_f32_e32 v76, v77, v76
	s_nop 5
	v_max3_f32 v77, v2, v3, v17
	v_max3_f32 v76, v76, v16, v18
	v_max3_f32 v76, v76, v19, v4
	v_max3_f32 v77, v77, v6, v7
	v_max3_f32 v76, v76, v5, v20
	v_max3_f32 v77, v77, v22, v23
	v_max3_f32 v76, v76, v21, v8
	v_max3_f32 v77, v77, v10, v11
	v_max3_f32 v76, v76, v9, v24
	v_max3_f32 v77, v77, v26, v27
	v_max3_f32 v76, v76, v25, v12
	v_max3_f32 v77, v77, v14, v15
	v_max3_f32 v76, v76, v13, v28
	v_max3_f32 v77, v77, v30, v31
	v_and_b32_e32 v78, 64, v183
	v_max3_f32 v76, v76, v29, v77
	v_xor_b32_e32 v77, 32, v183
	v_add_u32_e32 v78, 64, v78
	v_cmp_lt_i32_e32 vcc, v77, v78
	s_nop 1
	v_cndmask_b32_e32 v77, v183, v77, vcc
	v_lshlrev_b32_e32 v77, 2, v77
	ds_bpermute_b32 v77, v77, v76
	s_waitcnt lgkmcnt(0)
	v_max_f32_e32 v77, v77, v77
	v_max_f32_e32 v82, v76, v77
	v_sub_f32_e32 v0, v0, v82
	v_sub_f32_e32 v1, v1, v82
	v_sub_f32_e32 v16, v16, v82
	v_sub_f32_e32 v17, v17, v82
	v_exp_f32_e32 v0, v0
	v_exp_f32_e32 v1, v1
	v_sub_f32_e32 v76, v28, v82
	v_sub_f32_e32 v77, v29, v82
	v_sub_f32_e32 v28, v2, v82
	v_sub_f32_e32 v29, v3, v82
	v_exp_f32_e32 v2, v16
	v_exp_f32_e32 v3, v17
	v_sub_f32_e32 v18, v18, v82
	v_sub_f32_e32 v19, v19, v82
	v_sub_f32_e32 v78, v30, v82
	v_sub_f32_e32 v79, v31, v82
	v_sub_f32_e32 v30, v4, v82
	v_sub_f32_e32 v31, v5, v82
	v_exp_f32_e32 v4, v28
	v_exp_f32_e32 v5, v29
	v_sub_f32_e32 v83, v6, v82
	v_sub_f32_e32 v120, v7, v82
	v_exp_f32_e32 v6, v18
	v_exp_f32_e32 v7, v19
	v_sub_f32_e32 v20, v20, v82
	v_sub_f32_e32 v21, v21, v82
	v_sub_f32_e32 v121, v8, v82
	v_sub_f32_e32 v122, v9, v82
	v_exp_f32_e32 v8, v30
	v_exp_f32_e32 v9, v31
	v_pk_add_f32 v[16:17], v[0:1], 0 op_sel_hi:[1,0]
	v_sub_f32_e32 v123, v10, v82
	v_sub_f32_e32 v131, v11, v82
	v_exp_f32_e32 v10, v20
	v_exp_f32_e32 v11, v21
	v_pk_add_f32 v[16:17], v[2:3], v[16:17]
	v_sub_f32_e32 v22, v22, v82
	v_sub_f32_e32 v23, v23, v82
	v_sub_f32_e32 v133, v12, v82
	v_sub_f32_e32 v134, v13, v82
	v_exp_f32_e32 v12, v83
	v_exp_f32_e32 v13, v120
	v_pk_add_f32 v[16:17], v[4:5], v[16:17]
	v_sub_f32_e32 v135, v14, v82
	v_sub_f32_e32 v136, v15, v82
	v_exp_f32_e32 v14, v22
	v_exp_f32_e32 v15, v23
	v_pk_add_f32 v[16:17], v[6:7], v[16:17]
	v_sub_f32_e32 v24, v24, v82
	v_sub_f32_e32 v25, v25, v82
	v_exp_f32_e32 v20, v121
	v_exp_f32_e32 v21, v122
	v_pk_add_f32 v[16:17], v[8:9], v[16:17]
	v_exp_f32_e32 v22, v24
	v_exp_f32_e32 v23, v25
	v_pk_add_f32 v[16:17], v[10:11], v[16:17]
	v_sub_f32_e32 v26, v26, v82
	v_sub_f32_e32 v27, v27, v82
	v_exp_f32_e32 v24, v123
	v_exp_f32_e32 v25, v131
	v_pk_add_f32 v[16:17], v[12:13], v[16:17]
	v_exp_f32_e32 v26, v26
	v_exp_f32_e32 v27, v27
	v_pk_add_f32 v[16:17], v[14:15], v[16:17]
	v_exp_f32_e32 v28, v133
	v_exp_f32_e32 v29, v134
	v_pk_add_f32 v[16:17], v[20:21], v[16:17]
	v_exp_f32_e32 v30, v76
	v_exp_f32_e32 v31, v77
	v_pk_add_f32 v[16:17], v[22:23], v[16:17]
	v_exp_f32_e32 v76, v135
	v_exp_f32_e32 v77, v136
	v_pk_add_f32 v[16:17], v[24:25], v[16:17]
	v_exp_f32_e32 v134, v78
	v_exp_f32_e32 v135, v79
	v_pk_add_f32 v[16:17], v[26:27], v[16:17]
	v_cvt_pk_bf16_f32 v18, v8, v9
	v_pk_add_f32 v[16:17], v[28:29], v[16:17]
	v_cvt_pk_bf16_f32 v19, v12, v13
	v_pk_add_f32 v[16:17], v[30:31], v[16:17]
	v_cvt_pk_bf16_f32 v120, v2, v3
	v_pk_add_f32 v[16:17], v[76:77], v[16:17]
	v_cvt_pk_bf16_f32 v121, v6, v7
	v_pk_add_f32 v[140:141], v[134:135], v[16:17]
	v_cvt_pk_bf16_f32 v16, v0, v1
	v_cvt_pk_bf16_f32 v17, v4, v5
	v_cvt_pk_bf16_f32 v122, v10, v11
	v_cvt_pk_bf16_f32 v123, v14, v15
	v_cvt_pk_bf16_f32 v136, v20, v21
	v_cvt_pk_bf16_f32 v137, v24, v25
	v_cvt_pk_bf16_f32 v138, v28, v29
	v_cvt_pk_bf16_f32 v139, v76, v77
	v_cvt_pk_bf16_f32 v76, v22, v23
	v_cvt_pk_bf16_f32 v77, v26, v27
	v_cvt_pk_bf16_f32 v78, v30, v31
	v_mfma_f32_32x32x16_bf16 v[0:15], v[16:19], v[72:75], 0
	v_cvt_pk_bf16_f32 v79, v134, v135
	v_add_f32_e64 v134, v140, v140
	v_add_f32_e64 v135, v140, v141
	v_mov_b32_e32 v83, v135
	v_add_f32_e64 v82, v82, 0
	v_add_f32_e64 v83, v83, 0
	v_mfma_f32_32x32x16_bf16 v[16:31], v[16:19], v[68:71], 0
	v_mfma_f32_32x32x16_bf16 v[0:15], v[136:139], v[64:67], v[0:15]
	v_mfma_f32_32x32x16_bf16 v[16:31], v[136:139], v[60:63], v[16:31]
	v_mfma_f32_32x32x16_bf16 v[0:15], v[120:123], v[44:47], v[0:15]
	v_mfma_f32_32x32x16_bf16 v[16:31], v[120:123], v[40:43], v[16:31]
	v_mfma_f32_32x32x16_bf16 v[0:15], v[76:79], v[36:39], v[0:15]
	v_mfma_f32_32x32x16_bf16 v[16:31], v[76:79], v[32:35], v[16:31]
	v_xor_b32_e32 v32, 0x80000000, v82
	v_mov_b32_e32 v33, v32
	v_mov_b32_e32 v34, v32
	v_mov_b32_e32 v35, v32
	v_mov_b32_e32 v36, v32
	v_mov_b32_e32 v37, v32
	v_mov_b32_e32 v38, v32
	v_mov_b32_e32 v39, v32
	v_mov_b32_e32 v40, v32
	v_mov_b32_e32 v41, v32
	v_mov_b32_e32 v42, v32
	v_mov_b32_e32 v43, v32
	v_mov_b32_e32 v44, v32
	v_mov_b32_e32 v45, v32
	v_mov_b32_e32 v46, v32
	v_mov_b32_e32 v47, v32
	ds_write_b128 v187, v[52:55] offset:13312
	s_and_saveexec_b64 s[46:47], s[44:45]
	s_cbranch_execnz .LBB0_738
	s_branch .LBB0_739

.LBB0_739:
	s_or_b64 exec, exec, s[46:47]
	s_lshl_b32 s16, s64, 2
	s_add_i32 s16, s16, 0
	s_lshl_b64 s[50:51], s[50:51], 1
	v_mad_i64_i32 v[48:49], s[46:47], v127, s37, 0
	v_mov_b32_e32 v133, v81
	s_add_u32 s50, s14, s50
	v_lshl_add_u64 v[48:49], v[48:49], 0, v[132:133]
	s_addc_u32 s51, s15, s51
	s_waitcnt vmcnt(1)
	v_mov_b64_e32 v[122:123], v[110:111]
	s_mov_b32 s67, 0
	v_cmp_eq_u32_e64 s[46:47], 0, v185
	v_lshl_add_u32 v190, v186, 2, s16
	v_mad_u64_u32 v[170:171], s[68:69], v130, 6, v[128:129]
	v_mov_b32_e32 v169, v81
	v_lshl_add_u64 v[172:173], s[50:51], 0, v[48:49]
	v_mad_u64_u32 v[174:175], s[50:51], v126, 6, v[124:125]
	v_mov_b64_e32 v[120:121], v[108:109]
	v_add_u32_e32 v191, 0x2400, v188
	ds_write2_b64 v191, v[56:57], v[58:59] offset1:2
	s_waitcnt lgkmcnt(0)
	s_barrier
	s_waitcnt vmcnt(0)
	global_load_dwordx4 v[124:127], v[174:175], off
	s_and_saveexec_b64 s[50:51], s[44:45]
	s_cbranch_execz .LBB0_742
	s_branch .LBB0_741

.LBB0_742:
	s_or_b64 exec, exec, s[50:51]
	global_load_dwordx4 v[128:131], v[172:173], off
	s_add_i32 s67, s67, 1
	s_and_b32 s68, s67, 1
	s_cmp_gt_i32 s67, s66
	s_cbranch_scc1 .Latt_wonly
	s_mul_i32 s50, s68, 0x3400
	v_add_u32_e32 v52, s50, v189
	ds_read_b128 v[48:51], v52
	ds_read_b128 v[132:135], v52 offset:32
	ds_read_b128 v[136:139], v52 offset:6656
	ds_read_b128 v[140:143], v52 offset:6688
	ds_read_b128 v[144:147], v52 offset:64
	ds_read_b128 v[148:151], v52 offset:96
	ds_read_b128 v[152:155], v52 offset:6720
	ds_read_b128 v[156:159], v52 offset:6752
	ds_read_b128 v[160:163], v52 offset:128
	ds_read_b128 v[192:195], v52 offset:160
	ds_read_b128 v[196:199], v52 offset:6784
	ds_read_b128 v[200:203], v52 offset:6816
	s_waitcnt lgkmcnt(11)
	v_mfma_f32_32x32x16_bf16 v[64:79], v[48:51], v[104:107], v[32:47]
	s_mul_i32 s50, s68, 0x2400
	s_waitcnt lgkmcnt(9)
	v_mfma_f32_32x32x16_bf16 v[48:63], v[136:139], v[104:107], v[32:47]
	v_mfma_f32_32x32x16_bf16 v[64:79], v[132:135], v[100:103], v[64:79]
	v_add_u32_e32 v132, s50, v165
	v_add_u32_e32 v133, 0x6800, v132
	v_add_u32_e32 v132, 0x7800, v132
	s_waitcnt lgkmcnt(8)
	v_mfma_f32_32x32x16_bf16 v[48:63], v[140:143], v[100:103], v[48:63]
	s_waitcnt lgkmcnt(7)
	v_mfma_f32_32x32x16_bf16 v[64:79], v[144:147], v[96:99], v[64:79]
	s_waitcnt lgkmcnt(5)
	v_mfma_f32_32x32x16_bf16 v[48:63], v[152:155], v[96:99], v[48:63]
	ds_read_b128 v[152:155], v133 offset:32
	v_mfma_f32_32x32x16_bf16 v[64:79], v[148:151], v[92:95], v[64:79]
	s_waitcnt lgkmcnt(5)
	v_mfma_f32_32x32x16_bf16 v[48:63], v[156:159], v[92:95], v[48:63]
	s_waitcnt lgkmcnt(4)
	v_mfma_f32_32x32x16_bf16 v[64:79], v[160:163], v[88:91], v[64:79]
	ds_read_b128 v[160:163], v133
	ds_read_b128 v[156:159], v132 offset:512
	ds_read_b128 v[148:151], v132 offset:544
	ds_read_b128 v[144:147], v133 offset:64
	ds_read_b128 v[140:143], v132 offset:576
	ds_read_b128 v[136:139], v133 offset:96
	ds_read_b128 v[132:135], v132 offset:608
	s_waitcnt lgkmcnt(9)
	v_mfma_f32_32x32x16_bf16 v[48:63], v[196:199], v[88:91], v[48:63]
	v_mfma_f32_32x32x16_bf16 v[64:79], v[192:195], v[84:87], v[64:79]
	s_waitcnt lgkmcnt(8)
	v_mfma_f32_32x32x16_bf16 v[48:63], v[200:203], v[84:87], v[48:63]
	s_xor_b32 s68, s68, 1
	s_mul_i32 s69, s68, 0x3400
	v_add_u32_e32 v191, s69, v187
	ds_write_b128 v191, v[112:115]
	s_and_saveexec_b64 s[50:51], s[44:45]
	v_add_u32_e32 v191, s69, v167
	ds_write_b128 v191, v[108:111]
	s_or_b64 exec, exec, s[50:51]
	s_mulk_i32 s68, 0x2400
	v_add_u32_e32 v191, s68, v188
	v_lshl_add_u64 v[170:171], v[170:171], 0, v[168:169]
	v_lshl_add_u64 v[172:173], v[172:173], 0, s[18:19]
	v_lshl_add_u64 v[174:175], v[174:175], 0, v[80:81]
	ds_write2_b64 v191, v[116:117], v[118:119] offset1:2
	v_max_f32_e32 v191, v65, v65
	v_max_f32_e32 v192, v64, v64
	v_max_f32_e32 v191, v192, v191
	v_max3_f32 v192, v66, v67, v49
	v_max3_f32 v191, v191, v48, v50
	v_max3_f32 v191, v191, v51, v68
	v_max3_f32 v192, v192, v70, v71
	v_max3_f32 v191, v191, v69, v52
	v_max3_f32 v192, v192, v54, v55
	v_max3_f32 v191, v191, v53, v72
	v_max3_f32 v192, v192, v74, v75
	v_max3_f32 v191, v191, v73, v56
	v_max3_f32 v192, v192, v58, v59
	v_max3_f32 v191, v191, v57, v76
	v_max3_f32 v192, v192, v78, v79
	v_max3_f32 v191, v191, v77, v60
	v_max3_f32 v192, v192, v62, v63
	v_max3_f32 v191, v191, v61, v192
	v_mov_b32_e32 v192, v191
	s_nop 1
	v_permlane32_swap_b32_e32 v191, v192
	v_max_f32_e32 v191, v191, v192
	v_cmp_lt_f32_e32 vcc, s3, v191
	s_cbranch_vccz .LBB0_747
	v_max_f32_e32 v32, v191, v191
	v_max_f32_e32 v34, 0, v32
	v_exp_f32_e64 v191, -v34
	s_and_saveexec_b64 s[50:51], s[46:47]
	ds_write_b32 v190, v191 offset:45056
	s_or_b64 exec, exec, s[50:51]
	v_add_u32_e32 v47, s16, v166
	ds_read_b128 v[192:195], v47 offset:45120
	ds_read_b128 v[196:199], v47 offset:45152
	ds_read_b128 v[200:203], v47 offset:45056
	ds_read_b128 v[204:207], v47 offset:45088
	v_add_f32_e32 v82, v82, v34
	v_xor_b32_e32 v32, 0x80000000, v82
	v_pk_add_f32 v[64:65], v[64:65], v[34:35] op_sel_hi:[1,0] neg_lo:[0,1] neg_hi:[0,1]
	v_pk_add_f32 v[48:49], v[48:49], v[34:35] op_sel_hi:[1,0] neg_lo:[0,1] neg_hi:[0,1]
	v_pk_add_f32 v[66:67], v[66:67], v[34:35] op_sel_hi:[1,0] neg_lo:[0,1] neg_hi:[0,1]
	v_pk_add_f32 v[50:51], v[50:51], v[34:35] op_sel_hi:[1,0] neg_lo:[0,1] neg_hi:[0,1]
	v_pk_add_f32 v[68:69], v[68:69], v[34:35] op_sel_hi:[1,0] neg_lo:[0,1] neg_hi:[0,1]
	v_pk_add_f32 v[52:53], v[52:53], v[34:35] op_sel_hi:[1,0] neg_lo:[0,1] neg_hi:[0,1]
	v_pk_add_f32 v[70:71], v[70:71], v[34:35] op_sel_hi:[1,0] neg_lo:[0,1] neg_hi:[0,1]
	v_pk_add_f32 v[54:55], v[54:55], v[34:35] op_sel_hi:[1,0] neg_lo:[0,1] neg_hi:[0,1]
	v_pk_add_f32 v[72:73], v[72:73], v[34:35] op_sel_hi:[1,0] neg_lo:[0,1] neg_hi:[0,1]
	v_pk_add_f32 v[56:57], v[56:57], v[34:35] op_sel_hi:[1,0] neg_lo:[0,1] neg_hi:[0,1]
	v_pk_add_f32 v[74:75], v[74:75], v[34:35] op_sel_hi:[1,0] neg_lo:[0,1] neg_hi:[0,1]
	v_pk_add_f32 v[58:59], v[58:59], v[34:35] op_sel_hi:[1,0] neg_lo:[0,1] neg_hi:[0,1]
	v_pk_add_f32 v[76:77], v[76:77], v[34:35] op_sel_hi:[1,0] neg_lo:[0,1] neg_hi:[0,1]
	v_pk_add_f32 v[60:61], v[60:61], v[34:35] op_sel_hi:[1,0] neg_lo:[0,1] neg_hi:[0,1]
	v_pk_add_f32 v[78:79], v[78:79], v[34:35] op_sel_hi:[1,0] neg_lo:[0,1] neg_hi:[0,1]
	v_pk_add_f32 v[62:63], v[62:63], v[34:35] op_sel_hi:[1,0] neg_lo:[0,1] neg_hi:[0,1]
	v_mov_b32_e32 v33, v32
	v_mov_b32_e32 v34, v32
	v_mov_b32_e32 v35, v32
	v_mov_b32_e32 v36, v32
	v_mov_b32_e32 v37, v32
	v_mov_b32_e32 v38, v32
	v_mov_b32_e32 v39, v32
	v_mov_b32_e32 v40, v32
	v_mov_b32_e32 v41, v32
	v_mov_b32_e32 v42, v32
	v_mov_b32_e32 v43, v32
	v_mov_b32_e32 v44, v32
	v_mov_b32_e32 v45, v32
	v_mov_b32_e32 v46, v32
	v_mov_b32_e32 v47, v32
	v_mul_f32_e32 v83, v83, v191
	s_waitcnt lgkmcnt(2)
	v_pk_mul_f32 v[12:13], v[12:13], v[196:197]
	v_pk_mul_f32 v[8:9], v[8:9], v[192:193]
	s_waitcnt lgkmcnt(0)
	v_pk_mul_f32 v[4:5], v[4:5], v[204:205]
	v_pk_mul_f32 v[14:15], v[14:15], v[198:199]
	v_pk_mul_f32 v[10:11], v[10:11], v[194:195]
	v_pk_mul_f32 v[6:7], v[6:7], v[206:207]
	v_pk_mul_f32 v[2:3], v[2:3], v[202:203]
	v_pk_mul_f32 v[0:1], v[0:1], v[200:201]
	v_pk_mul_f32 v[28:29], v[28:29], v[196:197]
	v_pk_mul_f32 v[24:25], v[24:25], v[192:193]
	v_pk_mul_f32 v[20:21], v[20:21], v[204:205]
	v_pk_mul_f32 v[30:31], v[30:31], v[198:199]
	v_pk_mul_f32 v[26:27], v[26:27], v[194:195]
	v_pk_mul_f32 v[22:23], v[22:23], v[206:207]
	v_pk_mul_f32 v[18:19], v[18:19], v[202:203]
	v_pk_mul_f32 v[16:17], v[16:17], v[200:201]
.LBB0_747:
	v_exp_f32_e32 v192, v64
	v_exp_f32_e32 v193, v65
	v_exp_f32_e32 v194, v66
	v_exp_f32_e32 v195, v67
	v_exp_f32_e32 v196, v68
	v_exp_f32_e32 v197, v69
	v_exp_f32_e32 v198, v70
	v_exp_f32_e32 v199, v71
	v_cvt_pk_bf16_f32 v64, v192, v193
	v_cvt_pk_bf16_f32 v65, v194, v195
	v_cvt_pk_bf16_f32 v66, v196, v197
	v_cvt_pk_bf16_f32 v67, v198, v199
	v_exp_f32_e32 v72, v72
	v_exp_f32_e32 v73, v73
	v_exp_f32_e32 v74, v74
	v_exp_f32_e32 v75, v75
	v_exp_f32_e32 v76, v76
	v_exp_f32_e32 v77, v77
	v_exp_f32_e32 v78, v78
	v_exp_f32_e32 v79, v79
	s_waitcnt lgkmcnt(0)
	v_mfma_f32_32x32x16_bf16 v[0:15], v[64:67], v[160:163], v[0:15]
	v_cvt_pk_bf16_f32 v68, v72, v73
	v_cvt_pk_bf16_f32 v69, v74, v75
	v_cvt_pk_bf16_f32 v70, v76, v77
	v_cvt_pk_bf16_f32 v71, v78, v79
	v_exp_f32_e32 v200, v48
	v_exp_f32_e32 v201, v49
	v_exp_f32_e32 v52, v52
	v_mfma_f32_32x32x16_bf16 v[16:31], v[64:67], v[156:159], v[16:31]
	v_exp_f32_e32 v64, v50
	v_exp_f32_e32 v65, v51
	v_exp_f32_e32 v53, v53
	v_exp_f32_e32 v66, v54
	v_exp_f32_e32 v67, v55
	v_cvt_pk_bf16_f32 v48, v200, v201
	v_cvt_pk_bf16_f32 v49, v64, v65
	v_mfma_f32_32x32x16_bf16 v[0:15], v[68:71], v[152:155], v[0:15]
	v_cvt_pk_bf16_f32 v50, v52, v53
	v_cvt_pk_bf16_f32 v51, v66, v67
	v_add_f32_e64 v54, v192, 0
	v_add_f32_e64 v55, v193, 0
	v_exp_f32_e32 v56, v56
	v_exp_f32_e32 v57, v57
	v_exp_f32_e32 v58, v58
	v_exp_f32_e32 v59, v59
	v_mfma_f32_32x32x16_bf16 v[16:31], v[68:71], v[148:151], v[16:31]
	v_exp_f32_e32 v60, v60
	v_exp_f32_e32 v61, v61
	v_exp_f32_e32 v62, v62
	v_exp_f32_e32 v63, v63
	v_pk_add_f32 v[54:55], v[200:201], v[54:55]
	s_nop 0
	v_pk_add_f32 v[54:55], v[194:195], v[54:55]
	v_mfma_f32_32x32x16_bf16 v[0:15], v[48:51], v[144:147], v[0:15]
	v_add_f32_e64 v54, v64, v54
	v_add_f32_e64 v55, v65, v55
	v_add_f32_e64 v54, v196, v54
	v_add_f32_e64 v55, v197, v55
	v_add_f32_e64 v64, v52, v54
	v_add_f32_e64 v65, v53, v55
	v_cvt_pk_bf16_f32 v52, v56, v57
	v_cvt_pk_bf16_f32 v53, v58, v59
	v_mfma_f32_32x32x16_bf16 v[16:31], v[48:51], v[140:143], v[16:31]
	v_cvt_pk_bf16_f32 v54, v60, v61
	v_cvt_pk_bf16_f32 v55, v62, v63
	v_add_f32_e64 v48, v198, v64
	v_add_f32_e64 v49, v199, v65
	v_add_f32_e64 v48, v66, v48
	v_add_f32_e64 v49, v67, v49
	v_pk_add_f32 v[48:49], v[72:73], v[48:49]
	v_mfma_f32_32x32x16_bf16 v[0:15], v[52:55], v[136:139], v[0:15]
	v_add_f32_e64 v48, v56, v48
	v_add_f32_e64 v49, v57, v49
	v_add_f32_e64 v48, v74, v48
	v_add_f32_e64 v49, v75, v49
	v_add_f32_e64 v48, v58, v48
	v_add_f32_e64 v49, v59, v49
	v_pk_add_f32 v[48:49], v[76:77], v[48:49]
	v_mfma_f32_32x32x16_bf16 v[16:31], v[52:55], v[132:135], v[16:31]
	v_add_f32_e64 v48, v60, v48
	v_add_f32_e64 v49, v61, v49
	v_add_f32_e64 v48, v78, v48
	v_add_f32_e64 v49, v79, v49
	v_add_f32_e64 v48, v62, v48
	v_add_f32_e64 v49, v63, v49
	v_add_f32_e32 v48, v48, v49
	v_add_f32_e32 v83, v83, v48
.Latt_end:
	s_cmp_eq_u32 s65, s67
	s_waitcnt lgkmcnt(0)
	s_barrier
	s_cbranch_scc0 .LBB0_740
	s_branch .Latt_after
.Latt_wonly:
	s_xor_b32 s68, s68, 1
	s_mul_i32 s69, s68, 0x3400
	v_add_u32_e32 v191, s69, v187
	ds_write_b128 v191, v[112:115]
	s_and_saveexec_b64 s[50:51], s[44:45]
	v_add_u32_e32 v191, s69, v167
	ds_write_b128 v191, v[108:111]
	s_or_b64 exec, exec, s[50:51]
	s_mulk_i32 s68, 0x2400
	v_add_u32_e32 v191, s68, v188
	v_lshl_add_u64 v[170:171], v[170:171], 0, v[168:169]
	v_lshl_add_u64 v[172:173], v[172:173], 0, s[18:19]
	v_lshl_add_u64 v[174:175], v[174:175], 0, v[80:81]
	ds_write2_b64 v191, v[116:117], v[118:119] offset1:2
	s_branch .Latt_end
.Latt_after:
	s_add_i32 s67, s67, 1
	s_and_b32 s68, s67, 1
	s_cmp_ge_i32 s65, s66
	s_cbranch_scc1 .LBB0_757
	s_mul_i32 s50, s68, 0x3400
	v_add_u32_e32 v52, s50, v189
	ds_read_b128 v[48:51], v52
	ds_read_b128 v[108:111], v52 offset:32
	ds_read_b128 v[112:115], v52 offset:6656
	ds_read_b128 v[116:119], v52 offset:6688
	ds_read_b128 v[132:135], v52 offset:64
	ds_read_b128 v[136:139], v52 offset:96
	ds_read_b128 v[140:143], v52 offset:6720
	ds_read_b128 v[144:147], v52 offset:6752
	ds_read_b128 v[148:151], v52 offset:128
	ds_read_b128 v[152:155], v52 offset:160
	ds_read_b128 v[156:159], v52 offset:6784
	ds_read_b128 v[160:163], v52 offset:6816
	s_waitcnt lgkmcnt(11)
	v_mfma_f32_32x32x16_bf16 v[64:79], v[48:51], v[104:107], v[32:47]
	s_mul_i32 s50, s68, 0x2400
	v_add_u32_e32 v80, s50, v165
	s_waitcnt lgkmcnt(9)
	v_mfma_f32_32x32x16_bf16 v[48:63], v[112:115], v[104:107], v[32:47]
	v_mfma_f32_32x32x16_bf16 v[64:79], v[108:111], v[100:103], v[64:79]
	v_add_u32_e32 v108, 0x6800, v80
	v_add_u32_e32 v80, 0x7800, v80
	s_waitcnt lgkmcnt(8)
	v_mfma_f32_32x32x16_bf16 v[48:63], v[116:119], v[100:103], v[48:63]
	s_waitcnt lgkmcnt(7)
	v_mfma_f32_32x32x16_bf16 v[64:79], v[132:135], v[96:99], v[64:79]
	s_waitcnt lgkmcnt(5)
	v_mfma_f32_32x32x16_bf16 v[48:63], v[140:143], v[96:99], v[48:63]
	ds_read_b128 v[140:143], v108 offset:32
	v_mfma_f32_32x32x16_bf16 v[64:79], v[136:139], v[92:95], v[64:79]
	s_waitcnt lgkmcnt(5)
	v_mfma_f32_32x32x16_bf16 v[48:63], v[144:147], v[92:95], v[48:63]
	s_waitcnt lgkmcnt(4)
	v_mfma_f32_32x32x16_bf16 v[64:79], v[148:151], v[88:91], v[64:79]
	ds_read_b128 v[148:151], v108
	ds_read_b128 v[144:147], v80 offset:512
	ds_read_b128 v[136:139], v80 offset:544
	ds_read_b128 v[132:135], v108 offset:64
	ds_read_b128 v[116:119], v80 offset:576
	ds_read_b128 v[112:115], v108 offset:96
	ds_read_b128 v[108:111], v80 offset:608
	s_waitcnt lgkmcnt(9)
	v_mfma_f32_32x32x16_bf16 v[48:63], v[156:159], v[88:91], v[48:63]
	v_mfma_f32_32x32x16_bf16 v[64:79], v[152:155], v[84:87], v[64:79]
	s_waitcnt lgkmcnt(8)
	v_mfma_f32_32x32x16_bf16 v[48:63], v[160:163], v[84:87], v[48:63]
	s_nop 9
	v_max_f32_e32 v80, v65, v65
	v_max_f32_e32 v152, v64, v64
	v_max_f32_e32 v80, v152, v80
	v_max3_f32 v152, v66, v67, v49
	v_max3_f32 v80, v80, v48, v50
	v_max3_f32 v80, v80, v51, v68
	v_max3_f32 v152, v152, v70, v71
	v_max3_f32 v80, v80, v69, v52
	v_max3_f32 v152, v152, v54, v55
	v_max3_f32 v80, v80, v53, v72
	v_max3_f32 v152, v152, v74, v75
	v_max3_f32 v80, v80, v73, v56
	v_max3_f32 v152, v152, v58, v59
	v_max3_f32 v80, v80, v57, v76
	v_max3_f32 v152, v152, v78, v79
	v_max3_f32 v80, v80, v77, v60
	v_max3_f32 v152, v152, v62, v63
	v_and_b32_e32 v153, 64, v183
	v_max3_f32 v80, v80, v61, v152
	v_xor_b32_e32 v152, 32, v183
	v_add_u32_e32 v153, 64, v153
	v_cmp_lt_i32_e32 vcc, v152, v153
	s_nop 1
	v_cndmask_b32_e32 v152, v183, v152, vcc
	v_lshlrev_b32_e32 v152, 2, v152
	ds_bpermute_b32 v152, v152, v80
	s_waitcnt lgkmcnt(0)
	v_max_f32_e32 v152, v152, v152
	v_max_f32_e32 v80, v80, v152
	v_cmp_lt_f32_e32 vcc, s3, v80
	s_cbranch_vccz .LBB0_756
	v_max_f32_e32 v32, v80, v80
	v_max_f32_e32 v34, 0, v32
	v_exp_f32_e64 v80, -v34
	s_and_saveexec_b64 s[50:51], s[46:47]
	ds_write_b32 v190, v80 offset:45056
	s_or_b64 exec, exec, s[50:51]
	v_add_u32_e32 v47, s16, v166
	ds_read_b128 v[152:155], v47 offset:45120
	ds_read_b128 v[156:159], v47 offset:45152
	ds_read_b128 v[160:163], v47 offset:45056
	ds_read_b128 v[168:171], v47 offset:45088
	v_add_f32_e32 v32, v82, v34
	v_xor_b32_e32 v32, 0x80000000, v32
	v_pk_add_f32 v[64:65], v[64:65], v[34:35] op_sel_hi:[1,0] neg_lo:[0,1] neg_hi:[0,1]
	v_pk_add_f32 v[48:49], v[48:49], v[34:35] op_sel_hi:[1,0] neg_lo:[0,1] neg_hi:[0,1]
	v_pk_add_f32 v[66:67], v[66:67], v[34:35] op_sel_hi:[1,0] neg_lo:[0,1] neg_hi:[0,1]
	v_pk_add_f32 v[50:51], v[50:51], v[34:35] op_sel_hi:[1,0] neg_lo:[0,1] neg_hi:[0,1]
	v_pk_add_f32 v[68:69], v[68:69], v[34:35] op_sel_hi:[1,0] neg_lo:[0,1] neg_hi:[0,1]
	v_pk_add_f32 v[52:53], v[52:53], v[34:35] op_sel_hi:[1,0] neg_lo:[0,1] neg_hi:[0,1]
	v_pk_add_f32 v[70:71], v[70:71], v[34:35] op_sel_hi:[1,0] neg_lo:[0,1] neg_hi:[0,1]
	v_pk_add_f32 v[54:55], v[54:55], v[34:35] op_sel_hi:[1,0] neg_lo:[0,1] neg_hi:[0,1]
	v_pk_add_f32 v[72:73], v[72:73], v[34:35] op_sel_hi:[1,0] neg_lo:[0,1] neg_hi:[0,1]
	v_pk_add_f32 v[56:57], v[56:57], v[34:35] op_sel_hi:[1,0] neg_lo:[0,1] neg_hi:[0,1]
	v_pk_add_f32 v[74:75], v[74:75], v[34:35] op_sel_hi:[1,0] neg_lo:[0,1] neg_hi:[0,1]
	v_pk_add_f32 v[58:59], v[58:59], v[34:35] op_sel_hi:[1,0] neg_lo:[0,1] neg_hi:[0,1]
	v_pk_add_f32 v[76:77], v[76:77], v[34:35] op_sel_hi:[1,0] neg_lo:[0,1] neg_hi:[0,1]
	v_pk_add_f32 v[60:61], v[60:61], v[34:35] op_sel_hi:[1,0] neg_lo:[0,1] neg_hi:[0,1]
	v_pk_add_f32 v[78:79], v[78:79], v[34:35] op_sel_hi:[1,0] neg_lo:[0,1] neg_hi:[0,1]
	v_pk_add_f32 v[62:63], v[62:63], v[34:35] op_sel_hi:[1,0] neg_lo:[0,1] neg_hi:[0,1]
	v_mov_b32_e32 v33, v32
	v_mov_b32_e32 v34, v32
	v_mov_b32_e32 v35, v32
	v_mov_b32_e32 v36, v32
	v_mov_b32_e32 v37, v32
	v_mov_b32_e32 v38, v32
	v_mov_b32_e32 v39, v32
	v_mov_b32_e32 v40, v32
	v_mov_b32_e32 v41, v32
	v_mov_b32_e32 v42, v32
	v_mov_b32_e32 v43, v32
	v_mov_b32_e32 v44, v32
	v_mov_b32_e32 v45, v32
	v_mov_b32_e32 v46, v32
	v_mov_b32_e32 v47, v32
	v_mul_f32_e32 v83, v83, v80
	s_waitcnt lgkmcnt(2)
	v_pk_mul_f32 v[12:13], v[12:13], v[156:157]
	v_pk_mul_f32 v[8:9], v[8:9], v[152:153]
	s_waitcnt lgkmcnt(0)
	v_pk_mul_f32 v[4:5], v[4:5], v[168:169]
	v_pk_mul_f32 v[14:15], v[14:15], v[158:159]
	v_pk_mul_f32 v[10:11], v[10:11], v[154:155]
	v_pk_mul_f32 v[6:7], v[6:7], v[170:171]
	v_pk_mul_f32 v[2:3], v[2:3], v[162:163]
	v_pk_mul_f32 v[0:1], v[0:1], v[160:161]
	v_pk_mul_f32 v[28:29], v[28:29], v[156:157]
	v_pk_mul_f32 v[24:25], v[24:25], v[152:153]
	v_pk_mul_f32 v[20:21], v[20:21], v[168:169]
	v_pk_mul_f32 v[30:31], v[30:31], v[158:159]
	v_pk_mul_f32 v[26:27], v[26:27], v[154:155]
	v_pk_mul_f32 v[22:23], v[22:23], v[170:171]
	v_pk_mul_f32 v[18:19], v[18:19], v[162:163]
	v_pk_mul_f32 v[16:17], v[16:17], v[160:161]

.LBB0_757:
	s_xor_b32 s68, s68, 1
	s_mul_i32 s69, s68, 0x3400
	v_add_u32_e32 v48, s69, v187
	s_waitcnt vmcnt(1)
	ds_write_b128 v48, v[124:127]
	s_and_saveexec_b64 s[50:51], s[44:45]
	v_add_u32_e32 v48, s69, v167
	ds_write_b128 v48, v[120:123]
	s_or_b64 exec, exec, s[50:51]
	s_mulk_i32 s68, 0x2400
	v_add_u32_e32 v48, s68, v188
	s_cmp_ge_i32 s67, s66
	s_waitcnt vmcnt(0)
	ds_write2_b64 v48, v[128:129], v[130:131] offset1:2
	s_waitcnt lgkmcnt(0)
	s_barrier
	s_cbranch_scc1 .LBB0_765
	s_and_b32 s44, s65, 1
	s_mul_i32 s45, s44, 0x3400
	v_add_u32_e32 v48, s45, v189
	ds_read_b128 v[64:67], v48
	ds_read_b128 v[68:71], v48 offset:32
	ds_read_b128 v[72:75], v48 offset:6656
	ds_read_b128 v[76:79], v48 offset:6688
	ds_read_b128 v[108:111], v48 offset:64
	ds_read_b128 v[112:115], v48 offset:96
	ds_read_b128 v[116:119], v48 offset:6720
	ds_read_b128 v[120:123], v48 offset:6752
	ds_read_b128 v[124:127], v48 offset:128
	ds_read_b128 v[128:131], v48 offset:160
	ds_read_b128 v[132:135], v48 offset:6784
	ds_read_b128 v[136:139], v48 offset:6816
	s_mulk_i32 s44, 0x2400
	s_waitcnt lgkmcnt(11)
	v_mfma_f32_32x32x16_bf16 v[48:63], v[64:67], v[104:107], v[32:47]
	v_add_u32_e32 v64, s44, v165
	v_add_u32_e32 v65, 0x6800, v64
	v_add_u32_e32 v64, 0x7800, v64
	s_waitcnt lgkmcnt(9)
	v_mfma_f32_32x32x16_bf16 v[32:47], v[72:75], v[104:107], v[32:47]
	v_mfma_f32_32x32x16_bf16 v[48:63], v[68:71], v[100:103], v[48:63]
	s_waitcnt lgkmcnt(8)
	v_mfma_f32_32x32x16_bf16 v[32:47], v[76:79], v[100:103], v[32:47]
	ds_read_b128 v[100:103], v65
	s_waitcnt lgkmcnt(8)
	v_mfma_f32_32x32x16_bf16 v[48:63], v[108:111], v[96:99], v[48:63]
	s_waitcnt lgkmcnt(6)
	v_mfma_f32_32x32x16_bf16 v[32:47], v[116:119], v[96:99], v[32:47]
	v_mfma_f32_32x32x16_bf16 v[48:63], v[112:115], v[92:95], v[48:63]
	s_waitcnt lgkmcnt(5)
	v_mfma_f32_32x32x16_bf16 v[32:47], v[120:123], v[92:95], v[32:47]
	ds_read_b128 v[92:95], v65 offset:32
	s_waitcnt lgkmcnt(5)
	v_mfma_f32_32x32x16_bf16 v[48:63], v[124:127], v[88:91], v[48:63]
	s_waitcnt lgkmcnt(3)
	v_mfma_f32_32x32x16_bf16 v[32:47], v[132:135], v[88:91], v[32:47]
	ds_read_b128 v[96:99], v64 offset:512
	ds_read_b128 v[88:91], v64 offset:544
	ds_read_b128 v[76:79], v65 offset:64
	ds_read_b128 v[72:75], v64 offset:576
	ds_read_b128 v[68:71], v65 offset:96
	ds_read_b128 v[64:67], v64 offset:608
	v_mfma_f32_32x32x16_bf16 v[48:63], v[128:131], v[84:87], v[48:63]
	s_waitcnt lgkmcnt(8)
	v_mfma_f32_32x32x16_bf16 v[32:47], v[136:139], v[84:87], v[32:47]
	s_nop 9
	v_max_f32_e32 v80, v49, v49
	v_max_f32_e32 v82, v48, v48
	v_max_f32_e32 v80, v82, v80
	v_max3_f32 v82, v50, v51, v33
	v_max3_f32 v80, v80, v32, v34
	v_max3_f32 v80, v80, v35, v52
	v_max3_f32 v82, v82, v54, v55
	v_max3_f32 v80, v80, v53, v36
	v_max3_f32 v82, v82, v38, v39
	v_max3_f32 v80, v80, v37, v56
	v_max3_f32 v82, v82, v58, v59
	v_max3_f32 v80, v80, v57, v40
	v_max3_f32 v82, v82, v42, v43
	v_max3_f32 v80, v80, v41, v60
	v_max3_f32 v82, v82, v62, v63
	v_max3_f32 v80, v80, v61, v44
	v_max3_f32 v82, v82, v46, v47
	v_and_b32_e32 v84, 64, v183
	v_max3_f32 v80, v80, v45, v82
	v_xor_b32_e32 v82, 32, v183
	v_add_u32_e32 v84, 64, v84
	v_cmp_lt_i32_e32 vcc, v82, v84
	s_nop 1
	v_cndmask_b32_e32 v82, v183, v82, vcc
	v_lshlrev_b32_e32 v82, 2, v82
	ds_bpermute_b32 v82, v82, v80
	s_waitcnt lgkmcnt(0)
	v_max_f32_e32 v82, v82, v82
	v_max_f32_e32 v80, v80, v82
	v_cmp_lt_f32_e32 vcc, s3, v80
	s_cbranch_vccz .LBB0_764
	v_max_f32_e32 v80, v80, v80
	v_max_f32_e32 v80, 0, v80
	v_exp_f32_e64 v82, -v80
	s_and_saveexec_b64 s[44:45], s[46:47]
	ds_write_b32 v190, v82 offset:45056
	s_or_b64 exec, exec, s[44:45]
	v_pk_add_f32 v[48:49], v[48:49], v[80:81] op_sel_hi:[1,0] neg_lo:[0,1] neg_hi:[0,1]
	v_pk_add_f32 v[32:33], v[32:33], v[80:81] op_sel_hi:[1,0] neg_lo:[0,1] neg_hi:[0,1]
	v_pk_add_f32 v[50:51], v[50:51], v[80:81] op_sel_hi:[1,0] neg_lo:[0,1] neg_hi:[0,1]
	v_pk_add_f32 v[34:35], v[34:35], v[80:81] op_sel_hi:[1,0] neg_lo:[0,1] neg_hi:[0,1]
	v_pk_add_f32 v[52:53], v[52:53], v[80:81] op_sel_hi:[1,0] neg_lo:[0,1] neg_hi:[0,1]
	v_pk_add_f32 v[36:37], v[36:37], v[80:81] op_sel_hi:[1,0] neg_lo:[0,1] neg_hi:[0,1]
	v_pk_add_f32 v[54:55], v[54:55], v[80:81] op_sel_hi:[1,0] neg_lo:[0,1] neg_hi:[0,1]
	v_pk_add_f32 v[38:39], v[38:39], v[80:81] op_sel_hi:[1,0] neg_lo:[0,1] neg_hi:[0,1]
	v_pk_add_f32 v[56:57], v[56:57], v[80:81] op_sel_hi:[1,0] neg_lo:[0,1] neg_hi:[0,1]
	v_pk_add_f32 v[40:41], v[40:41], v[80:81] op_sel_hi:[1,0] neg_lo:[0,1] neg_hi:[0,1]
	v_pk_add_f32 v[58:59], v[58:59], v[80:81] op_sel_hi:[1,0] neg_lo:[0,1] neg_hi:[0,1]
	v_pk_add_f32 v[42:43], v[42:43], v[80:81] op_sel_hi:[1,0] neg_lo:[0,1] neg_hi:[0,1]
	v_pk_add_f32 v[60:61], v[60:61], v[80:81] op_sel_hi:[1,0] neg_lo:[0,1] neg_hi:[0,1]
	v_pk_add_f32 v[44:45], v[44:45], v[80:81] op_sel_hi:[1,0] neg_lo:[0,1] neg_hi:[0,1]
	v_pk_add_f32 v[62:63], v[62:63], v[80:81] op_sel_hi:[1,0] neg_lo:[0,1] neg_hi:[0,1]
	v_pk_add_f32 v[46:47], v[46:47], v[80:81] op_sel_hi:[1,0] neg_lo:[0,1] neg_hi:[0,1]
	v_add_u32_e32 v80, s16, v166
	ds_read_b128 v[84:87], v80 offset:45056
	ds_read_b128 v[104:107], v80 offset:45088
	ds_read_b128 v[108:111], v80 offset:45120
	ds_read_b128 v[112:115], v80 offset:45152
	v_mul_f32_e32 v83, v83, v82
	s_waitcnt lgkmcnt(3)
	v_pk_mul_f32 v[2:3], v[2:3], v[86:87]
	s_waitcnt lgkmcnt(2)
	v_pk_mul_f32 v[4:5], v[4:5], v[104:105]
	s_waitcnt lgkmcnt(1)
	v_pk_mul_f32 v[8:9], v[8:9], v[108:109]
	s_waitcnt lgkmcnt(0)
	v_pk_mul_f32 v[12:13], v[12:13], v[112:113]
	v_pk_mul_f32 v[14:15], v[14:15], v[114:115]
	v_pk_mul_f32 v[10:11], v[10:11], v[110:111]
	v_pk_mul_f32 v[6:7], v[6:7], v[106:107]
	v_pk_mul_f32 v[0:1], v[0:1], v[84:85]
	v_pk_mul_f32 v[28:29], v[28:29], v[112:113]
	v_pk_mul_f32 v[24:25], v[24:25], v[108:109]
	v_pk_mul_f32 v[20:21], v[20:21], v[104:105]
	v_pk_mul_f32 v[30:31], v[30:31], v[114:115]
	v_pk_mul_f32 v[26:27], v[26:27], v[110:111]
	v_pk_mul_f32 v[22:23], v[22:23], v[106:107]
	v_pk_mul_f32 v[18:19], v[18:19], v[86:87]
	v_pk_mul_f32 v[16:17], v[16:17], v[84:85]

.LBB0_765:
	s_and_b64 vcc, exec, s[48:49]
	s_barrier
	s_cbranch_vccz .LBB0_716
	v_and_b32_e32 v33, 64, v183
	v_xor_b32_e32 v32, 32, v183
	v_add_u32_e32 v33, 64, v33
	v_cmp_lt_i32_e32 vcc, v32, v33
	s_nop 1
	v_cndmask_b32_e32 v32, v183, v32, vcc
	v_lshlrev_b32_e32 v32, 2, v32
	ds_bpermute_b32 v32, v32, v83
	s_and_saveexec_b64 s[44:45], s[46:47]
	s_cbranch_execz .LBB0_715
	s_waitcnt lgkmcnt(0)
	v_add_f32_e32 v32, v83, v32
	v_div_scale_f32 v33, s[46:47], v32, v32, 1.0
	v_rcp_f32_e32 v34, v33
	v_div_scale_f32 v35, vcc, 1.0, v32, 1.0
	v_fma_f32 v36, -v33, v34, 1.0
	v_fmac_f32_e32 v34, v36, v34
	v_mul_f32_e32 v36, v35, v34
	v_fma_f32 v37, -v33, v36, v35
	v_fmac_f32_e32 v36, v37, v34
	v_fma_f32 v33, -v33, v36, v35
	v_div_fmas_f32 v33, v33, v34, v36
	v_div_fixup_f32 v32, v33, v32, 1.0
	ds_write_b32 v190, v32 offset:45056
	s_branch .LBB0_715
